# hyena conv8 input loads: halo loads issued without intermediate waits (single wait at the consumer)
# speedup vs baseline: 1.0060x; 1.0060x over previous
; __device__ __forceinline__ float bf2f(bf16_t u) { return __uint_as_float((unsigned)u << 16); }
; __device__ __forceinline__ float bflo(unsigned w) { return __uint_as_float(w << 16); }
; __device__ __forceinline__ float bfhi(unsigned w) { return __uint_as_float(w & 0xffff0000u); }
; __device__ __forceinline__ void conv8(const bf16_t* p, int c, int n, float w0, float w1, float w2, float b, float (&o)[8]) {
;     const v4u v = *(const v4u*)(p + 8 * c);
;     const float um = c > 0 ? bf2f(p[8 * c - 1]) : 0.f, up = 8 * c + 8 < n ? bf2f(p[8 * c + 8]) : 0.f;
;     const float u0 = bflo(v.x), u1 = bfhi(v.x), u2 = bflo(v.y), u3 = bfhi(v.y), u4 = bflo(v.z), u5 = bfhi(v.z), u6 = bflo(v.w), u7 = bfhi(v.w);
;     o[0] = w0 * um + w1 * u0 + w2 * u1 + b; o[1] = w0 * u0 + w1 * u1 + w2 * u2 + b; o[2] = w0 * u1 + w1 * u2 + w2 * u3 + b; o[3] = w0 * u2 + w1 * u3 + w2 * u4 + b;
;     o[4] = w0 * u3 + w1 * u4 + w2 * u5 + b; o[5] = w0 * u4 + w1 * u5 + w2 * u6 + b; o[6] = w0 * u5 + w1 * u6 + w2 * u7 + b; o[7] = w0 * u6 + w1 * u7 + w2 * up + b;
; }
; __global__ void __launch_bounds__(NTHR, 2) fwd_mega(Args a) {
;     ...
;                     for (int k = 0; k < 2; ++k) { const int ch = 64 * (wave + 8 * k) + cw; float u0[8], u1[8];
;                         conv8(pv0, ch, 8192, wv0, wv1, wv2, bv, u0); conv8(pv1, ch, 8192, wv0, wv1, wv2, bv, u1);
; #pragma unroll
;                         for (int e = 0; e < 8; ++e) { X[PX(8 * ch + e)] = mk2(u0[e], u1[e]); X[PX(8192 + 8 * ch + e)] = mk2(0.f, 0.f); } }
.LBB0_532:
	s_or_b64 exec, exec, s[4:5]
	s_waitcnt vmcnt(0) lgkmcnt(0)
	v_lshlrev_b32_e32 v15, 16, v15
	v_lshlrev_b32_e32 v10, 16, v10
	v_lshlrev_b32_e32 v9, 16, v9
	v_lshlrev_b32_e32 v11, 16, v11
	v_and_b32_e32 v13, 0xffff0000, v4
	v_lshlrev_b32_e32 v12, 16, v4
	v_lshlrev_b32_e32 v150, 16, v5
	v_lshlrev_b32_e32 v151, 16, v6
	v_and_b32_e32 v153, 0xffff0000, v6
	v_mul_f32_e32 v4, v133, v15
	v_mul_f32_e32 v6, v125, v13
	v_and_b32_e32 v5, 0xffff0000, v5
	v_fmac_f32_e32 v4, v125, v12
	v_fmac_f32_e32 v6, v133, v12
	v_mul_f32_e32 v12, v125, v150
	v_fmac_f32_e32 v4, v124, v13
	v_fmac_f32_e32 v12, v133, v13
	v_mul_f32_e32 v13, v125, v5
	v_fmac_f32_e32 v13, v133, v150
	v_fmac_f32_e32 v13, v124, v151
	v_fmac_f32_e32 v6, v124, v150
	v_add_f32_e32 v150, v166, v13
	v_mul_f32_e32 v13, v125, v151
	v_fmac_f32_e32 v12, v124, v5
	v_fmac_f32_e32 v13, v133, v5
	v_mul_f32_e32 v5, v125, v153
	v_lshlrev_b32_e32 v171, 16, v7
	v_fmac_f32_e32 v5, v133, v151
	v_fmac_f32_e32 v5, v124, v171
	v_add_f32_e32 v170, v166, v5
	v_mul_f32_e32 v5, v125, v171
	v_and_b32_e32 v7, 0xffff0000, v7
	v_fmac_f32_e32 v5, v133, v153
	v_fmac_f32_e32 v5, v124, v7
	v_and_b32_e32 v176, 0xffff0000, v0
	v_lshlrev_b32_e32 v177, 16, v0
	v_add_f32_e32 v172, v166, v5
	v_mul_f32_e32 v5, v125, v7
	v_pk_mul_f32 v[178:179], v[124:125], v[176:177]
	v_fmac_f32_e32 v5, v133, v171
	v_fma_f32 v0, v133, v9, v179
	v_fmac_f32_e32 v5, v124, v10
	v_add_f32_e32 v0, v178, v0
	v_add_f32_e32 v174, v166, v5
	v_add_f32_e32 v5, v166, v0
	v_and_b32_e32 v0, 0xffff0000, v1
	v_lshlrev_b32_e32 v1, 16, v1
	v_mov_b32_e32 v178, v1
	v_mov_b32_e32 v179, v177
	v_pk_mul_f32 v[178:179], v[132:133], v[178:179]
	v_lshlrev_b32_e32 v177, 16, v2
	v_fma_f32 v7, v125, v176, v179
	v_add_f32_e32 v7, v178, v7
	v_pk_mul_f32 v[178:179], v[124:125], v[0:1]
	v_fmac_f32_e32 v13, v124, v153
	v_fma_f32 v9, v133, v176, v179
	v_add_f32_e32 v9, v178, v9
	v_mov_b32_e32 v178, v177
	v_mov_b32_e32 v179, v1
	v_pk_mul_f32 v[178:179], v[132:133], v[178:179]
	v_and_b32_e32 v176, 0xffff0000, v2
	v_fma_f32 v1, v125, v0, v179
	v_add_f32_e32 v1, v178, v1
	v_pk_mul_f32 v[178:179], v[124:125], v[176:177]
	v_add_f32_e32 v151, v166, v1
	v_fma_f32 v0, v133, v0, v179
	v_add_f32_e32 v0, v178, v0
	v_lshlrev_b32_e32 v1, 16, v3
	v_add_f32_e32 v153, v166, v0
	v_and_b32_e32 v0, 0xffff0000, v3
	v_mov_b32_e32 v2, v1
	v_mov_b32_e32 v3, v177
	v_pk_mul_f32 v[2:3], v[132:133], v[2:3]
	v_mov_b32_e32 v10, v1
	v_fma_f32 v3, v125, v176, v3
	v_add_f32_e32 v2, v2, v3
	v_add_f32_e32 v171, v166, v2
	v_pk_mul_f32 v[2:3], v[124:125], v[0:1]
	v_lshlrev_b32_e32 v1, 3, v8
	v_fma_f32 v3, v133, v176, v3
	v_add_f32_e32 v2, v2, v3
	v_add_f32_e32 v173, v166, v2
	v_pk_mul_f32 v[2:3], v[138:139], v[10:11]
	s_xor_b64 s[4:5], s[6:7], -1
	v_fma_f32 v0, v125, v0, v2
	v_add_f32_e32 v0, v0, v3
	v_add_f32_e32 v175, v166, v0
	v_and_b32_e32 v0, -8, v14
	v_add3_u32 v0, 0, v0, v1
	v_add_u32_e32 v1, 0x2000, v8
	v_ashrrev_i32_e32 v2, 6, v1
	v_lshlrev_b32_e32 v2, 3, v2
	v_lshlrev_b32_e32 v1, 3, v1
	s_mov_b32 s65, s64
	v_add_f32_e32 v4, v166, v4
	v_add3_u32 v1, 0, v2, v1
	v_mov_b64_e32 v[2:3], s[64:65]
	s_movk_i32 s10, 0x200
	s_mov_b64 s[6:7], 0
	s_and_b64 vcc, exec, s[4:5]
	v_add_f32_e32 v6, v166, v6
	v_add_f32_e32 v12, v166, v12
	v_add_f32_e32 v152, v166, v13
	v_add_f32_e32 v7, v166, v7
	v_add_f32_e32 v13, v166, v9
	ds_write_b64 v0, v[4:5]
	ds_write_b64 v1, v[2:3]
	ds_write_b64 v0, v[6:7] offset:8
	ds_write_b64 v1, v[2:3] offset:8
	ds_write_b64 v0, v[12:13] offset:16
	ds_write_b64 v1, v[2:3] offset:16
	ds_write_b64 v0, v[150:151] offset:24
	ds_write_b64 v1, v[2:3] offset:24
	ds_write_b64 v0, v[152:153] offset:32
	ds_write_b64 v1, v[2:3] offset:32
	ds_write_b64 v0, v[170:171] offset:40
	ds_write_b64 v1, v[2:3] offset:40
	ds_write_b64 v0, v[172:173] offset:48
	ds_write_b64 v1, v[2:3] offset:48
	ds_write_b64 v0, v[174:175] offset:56
	ds_write_b64 v1, v[2:3] offset:56
	s_cbranch_vccnz .LBB0_541
.LBB0_533:
	v_add_u32_e32 v14, s10, v158
	v_lshlrev_b32_e32 v8, 3, v14
	v_ashrrev_i32_e32 v9, 31, v8
	v_lshl_add_u64 v[0:1], v[8:9], 1, s[36:37]
	global_load_dwordx4 v[4:7], v[0:1], off
	v_cmp_lt_i32_e32 vcc, 0, v14
	v_mov_b32_e32 v10, 0
	v_mov_b32_e32 v15, 0
	s_and_saveexec_b64 s[4:5], vcc
	s_cbranch_execz .LBB0_535
	v_add_co_u32_e64 v2, s[46:47], -2, v0
	s_nop 1
	v_addc_co_u32_e64 v3, s[46:47], -1, v1, s[46:47]
	global_load_ushort v15, v[2:3], off
.LBB0_535:
	s_or_b64 exec, exec, s[4:5]
	v_cmp_gt_i32_e64 s[46:47], s57, v14
	s_and_saveexec_b64 s[4:5], s[46:47]
	s_cbranch_execz .LBB0_537
	global_load_ushort v10, v[0:1], off offset:16

; __device__ __forceinline__ float bf2f(bf16_t u) { return __uint_as_float((unsigned)u << 16); }
; __device__ __forceinline__ float bflo(unsigned w) { return __uint_as_float(w << 16); }
; __device__ __forceinline__ float bfhi(unsigned w) { return __uint_as_float(w & 0xffff0000u); }
; __device__ __forceinline__ void conv8(const bf16_t* p, int c, int n, float w0, float w1, float w2, float b, float (&o)[8]) {
;     const v4u v = *(const v4u*)(p + 8 * c);
;     const float um = c > 0 ? bf2f(p[8 * c - 1]) : 0.f, up = 8 * c + 8 < n ? bf2f(p[8 * c + 8]) : 0.f;
;     const float u0 = bflo(v.x), u1 = bfhi(v.x), u2 = bflo(v.y), u3 = bfhi(v.y), u4 = bflo(v.z), u5 = bfhi(v.z), u6 = bflo(v.w), u7 = bfhi(v.w);
;     o[0] = w0 * um + w1 * u0 + w2 * u1 + b; o[1] = w0 * u0 + w1 * u1 + w2 * u2 + b; o[2] = w0 * u1 + w1 * u2 + w2 * u3 + b; o[3] = w0 * u2 + w1 * u3 + w2 * u4 + b;
;     o[4] = w0 * u3 + w1 * u4 + w2 * u5 + b; o[5] = w0 * u4 + w1 * u5 + w2 * u6 + b; o[6] = w0 * u5 + w1 * u6 + w2 * u7 + b; o[7] = w0 * u6 + w1 * u7 + w2 * up + b;
; }
.LBB0_539:
	s_or_b64 exec, exec, s[4:5]
	s_and_saveexec_b64 s[4:5], s[46:47]
	s_cbranch_execz .LBB0_532
	global_load_ushort v11, v[12:13], off offset:16
	s_branch .LBB0_532

; __device__ __forceinline__ float bf2f(bf16_t u) { return __uint_as_float((unsigned)u << 16); }
; __device__ __forceinline__ float bflo(unsigned w) { return __uint_as_float(w << 16); }
; __device__ __forceinline__ float bfhi(unsigned w) { return __uint_as_float(w & 0xffff0000u); }
; __device__ __forceinline__ void conv8(const bf16_t* p, int c, int n, float w0, float w1, float w2, float b, float (&o)[8]) {
;     const v4u v = *(const v4u*)(p + 8 * c);
;     const float um = c > 0 ? bf2f(p[8 * c - 1]) : 0.f, up = 8 * c + 8 < n ? bf2f(p[8 * c + 8]) : 0.f;
;     const float u0 = bflo(v.x), u1 = bfhi(v.x), u2 = bflo(v.y), u3 = bfhi(v.y), u4 = bflo(v.z), u5 = bfhi(v.z), u6 = bflo(v.w), u7 = bfhi(v.w);
;     o[0] = w0 * um + w1 * u0 + w2 * u1 + b; o[1] = w0 * u0 + w1 * u1 + w2 * u2 + b; o[2] = w0 * u1 + w1 * u2 + w2 * u3 + b; o[3] = w0 * u2 + w1 * u3 + w2 * u4 + b;
;     o[4] = w0 * u3 + w1 * u4 + w2 * u5 + b; o[5] = w0 * u4 + w1 * u5 + w2 * u6 + b; o[6] = w0 * u5 + w1 * u6 + w2 * u7 + b; o[7] = w0 * u6 + w1 * u7 + w2 * up + b;
; }
; __global__ void __launch_bounds__(NTHR, 2) fwd_mega(Args a) {
;     ...
;                     for (int k = 0; k < 2; ++k) { const int ch = 64 * (wave + 8 * k) + cw; float a0_[8], a1_[8];
;                         conv8(pv0 + 256 * 8192, ch, 8192, wa0, wa1, wa2, ba, a0_); conv8(pv1 + 256 * 8192, ch, 8192, wa0, wa1, wa2, ba, a1_);
; #pragma unroll
;                         for (int e = 0; e < 8; ++e) { const cf cv = X[PX(8 * ch + e)]; X[PX(8 * ch + e)] = mk2(a0_[e] * cv.x, a1_[e] * cv.y); X[PX(8192 + 8 * ch + e)] = mk2(0.f, 0.f); } }
.LBB0_556:
	s_or_b64 exec, exec, s[10:11]
	s_waitcnt vmcnt(0) lgkmcnt(0)
	v_lshlrev_b32_e32 v15, 16, v15
	v_lshlrev_b32_e32 v13, 16, v13
	v_lshlrev_b32_e32 v14, 16, v14
	v_lshlrev_b32_e32 v9, 16, v9
	v_and_b32_e32 v11, 0xffff0000, v4
	v_lshlrev_b32_e32 v10, 16, v4
	v_lshlrev_b32_e32 v150, 16, v5
	v_lshlrev_b32_e32 v151, 16, v6
	v_and_b32_e32 v153, 0xffff0000, v6
	v_mul_f32_e32 v4, v167, v15
	v_mul_f32_e32 v6, v135, v11
	v_and_b32_e32 v5, 0xffff0000, v5
	v_fmac_f32_e32 v4, v135, v10
	v_fmac_f32_e32 v6, v167, v10
	v_mul_f32_e32 v10, v135, v150
	v_fmac_f32_e32 v4, v134, v11
	v_fmac_f32_e32 v10, v167, v11
	v_mul_f32_e32 v11, v135, v5
	v_fmac_f32_e32 v11, v167, v150
	v_fmac_f32_e32 v11, v134, v151
	v_fmac_f32_e32 v6, v134, v150
	v_add_f32_e32 v150, v168, v11
	v_mul_f32_e32 v11, v135, v151
	v_fmac_f32_e32 v10, v134, v5
	v_fmac_f32_e32 v11, v167, v5
	v_mul_f32_e32 v5, v135, v153
	v_lshlrev_b32_e32 v171, 16, v7
	v_fmac_f32_e32 v5, v167, v151
	v_fmac_f32_e32 v5, v134, v171
	v_add_f32_e32 v170, v168, v5
	v_mul_f32_e32 v5, v135, v171
	v_and_b32_e32 v7, 0xffff0000, v7
	v_fmac_f32_e32 v5, v167, v153
	v_and_b32_e32 v176, 0xffff0000, v0
	v_fmac_f32_e32 v5, v134, v7
	v_lshlrev_b32_e32 v179, 16, v0
	v_mov_b32_e32 v178, v176
	v_add_f32_e32 v172, v168, v5
	v_mul_f32_e32 v5, v135, v7
	v_pk_mul_f32 v[180:181], v[134:135], v[178:179]
	v_fmac_f32_e32 v5, v167, v171
	v_and_b32_e32 v177, 16, v0
	v_fma_f32 v0, v167, v14, v181
	v_fmac_f32_e32 v5, v134, v13
	v_add_f32_e32 v0, v180, v0
	v_and_b32_e32 v14, 0xffff0000, v1
	v_add_f32_e32 v174, v168, v5
	v_add_f32_e32 v5, v168, v0
	v_and_b32_e32 v15, 16, v1
	v_lshlrev_b32_e32 v1, 16, v1
	v_mov_b32_e32 v0, v14
	v_pk_mov_b32 v[180:181], v[0:1], v[176:177] op_sel:[1,0]
	v_fmac_f32_e32 v11, v134, v153
	v_pk_mul_f32 v[180:181], v[134:135], v[180:181]
	v_add_f32_e32 v152, v168, v11
	v_fma_f32 v7, v167, v179, v181
	v_pk_mul_f32 v[178:179], v[134:135], v[0:1]
	v_add_f32_e32 v7, v180, v7
	v_fma_f32 v0, v167, v176, v179
	v_add_f32_e32 v0, v178, v0
	v_add_f32_e32 v11, v168, v0
	v_and_b32_e32 v0, -8, v12
	v_lshlrev_b32_e32 v12, 3, v8
	v_add3_u32 v180, 0, v0, v12
	ds_read_b64 v[176:177], v180
	v_add_u32_e32 v0, 0x2000, v8
	v_ashrrev_i32_e32 v8, 6, v0
	v_add_f32_e32 v4, v168, v4
	v_lshlrev_b32_e32 v8, 3, v8
	v_lshlrev_b32_e32 v0, 3, v0
	s_mov_b32 s65, s64
	v_add3_u32 v181, 0, v8, v0
	s_waitcnt lgkmcnt(0)
	v_pk_mul_f32 v[4:5], v[4:5], v[176:177]
	v_mov_b64_e32 v[182:183], s[64:65]
	ds_write_b64 v180, v[4:5]
	ds_write_b64 v181, v[182:183]
	ds_read_b64 v[4:5], v180 offset:8
	v_add_f32_e32 v6, v168, v6
	v_add_f32_e32 v7, v168, v7
	v_and_b32_e32 v12, 0xffff0000, v2
	v_lshlrev_b32_e32 v177, 16, v2
	s_waitcnt lgkmcnt(0)
	v_pk_mul_f32 v[4:5], v[6:7], v[4:5]
	ds_write_b64 v180, v[4:5] offset:8
	ds_write_b64 v181, v[182:183] offset:8
	v_mov_b32_e32 v176, v12
	ds_read_b64 v[4:5], v180 offset:16
	v_pk_mov_b32 v[178:179], v[176:177], v[14:15] op_sel:[1,0]
	v_add_f32_e32 v10, v168, v10
	v_pk_mul_f32 v[6:7], v[134:135], v[178:179]
	v_and_b32_e32 v13, 16, v2
	v_fma_f32 v0, v167, v1, v7
	v_add_f32_e32 v0, v6, v0
	v_add_f32_e32 v151, v168, v0
	s_waitcnt lgkmcnt(0)
	v_pk_mul_f32 v[0:1], v[10:11], v[4:5]
	ds_write_b64 v180, v[0:1] offset:16
	ds_write_b64 v181, v[182:183] offset:16
	ds_read_b64 v[0:1], v180 offset:24
	v_pk_mul_f32 v[4:5], v[134:135], v[176:177]
	s_xor_b64 s[10:11], s[68:69], -1
	v_fma_f32 v2, v167, v14, v5
	v_add_f32_e32 v2, v4, v2
	s_waitcnt lgkmcnt(0)
	v_pk_mul_f32 v[0:1], v[150:151], v[0:1]
	ds_write_b64 v180, v[0:1] offset:24
	ds_write_b64 v181, v[182:183] offset:24
	ds_read_b64 v[0:1], v180 offset:32
	v_add_f32_e32 v153, v168, v2
	v_and_b32_e32 v2, 0xffff0000, v3
	v_lshlrev_b32_e32 v3, 16, v3
	v_pk_mov_b32 v[4:5], v[2:3], v[12:13] op_sel:[1,0]
	s_waitcnt lgkmcnt(0)
	v_pk_mul_f32 v[0:1], v[152:153], v[0:1]
	ds_write_b64 v180, v[0:1] offset:32
	ds_write_b64 v181, v[182:183] offset:32
	ds_read_b64 v[0:1], v180 offset:40
	v_pk_mul_f32 v[4:5], v[134:135], v[4:5]
	v_mov_b32_e32 v8, v2
	v_fma_f32 v5, v167, v177, v5
	v_add_f32_e32 v4, v4, v5
	v_add_f32_e32 v171, v168, v4
	s_waitcnt lgkmcnt(0)
	v_pk_mul_f32 v[0:1], v[170:171], v[0:1]
	ds_write_b64 v180, v[0:1] offset:40
	ds_write_b64 v181, v[182:183] offset:40
	ds_read_b64 v[0:1], v180 offset:48
	v_pk_mul_f32 v[4:5], v[134:135], v[2:3]
	s_movk_i32 s13, 0x200
	v_fma_f32 v5, v167, v12, v5
	v_add_f32_e32 v4, v4, v5
	v_add_f32_e32 v173, v168, v4
	s_waitcnt lgkmcnt(0)
	v_pk_mul_f32 v[0:1], v[172:173], v[0:1]
	ds_write_b64 v180, v[0:1] offset:48
	ds_write_b64 v181, v[182:183] offset:48
	ds_read_b64 v[0:1], v180 offset:56
	v_pk_mul_f32 v[4:5], v[140:141], v[8:9]
	s_mov_b64 s[68:69], 0
	v_fma_f32 v2, v167, v3, v4
	v_add_f32_e32 v2, v2, v5
	v_add_f32_e32 v175, v168, v2
	s_waitcnt lgkmcnt(0)
	v_pk_mul_f32 v[0:1], v[174:175], v[0:1]
	s_and_b64 vcc, exec, s[10:11]
	ds_write_b64 v180, v[0:1] offset:56
	ds_write_b64 v181, v[182:183] offset:56
	s_cbranch_vccnz .LBB0_565
.LBB0_557:
	v_add_u32_e32 v12, s13, v158
	v_lshlrev_b32_e32 v8, 3, v12
	v_ashrrev_i32_e32 v9, 31, v8
	v_lshl_add_u64 v[0:1], v[8:9], 1, s[4:5]
	global_load_dwordx4 v[4:7], v[0:1], off
	v_cmp_lt_i32_e32 vcc, 0, v12
	v_mov_b32_e32 v13, 0
	v_mov_b32_e32 v15, 0
	s_and_saveexec_b64 s[10:11], vcc
	s_cbranch_execz .LBB0_559
	v_add_co_u32_e64 v2, s[46:47], -2, v0
	s_nop 1
	v_addc_co_u32_e64 v3, s[46:47], -1, v1, s[46:47]
	global_load_ushort v15, v[2:3], off
.LBB0_559:
	s_or_b64 exec, exec, s[10:11]
	v_cmp_gt_i32_e64 s[46:47], s57, v12
	s_and_saveexec_b64 s[10:11], s[46:47]
	s_cbranch_execz .LBB0_561
	global_load_ushort v13, v[0:1], off offset:16

; __device__ __forceinline__ float bf2f(bf16_t u) { return __uint_as_float((unsigned)u << 16); }
; __device__ __forceinline__ float bflo(unsigned w) { return __uint_as_float(w << 16); }
; __device__ __forceinline__ float bfhi(unsigned w) { return __uint_as_float(w & 0xffff0000u); }
; __device__ __forceinline__ void conv8(const bf16_t* p, int c, int n, float w0, float w1, float w2, float b, float (&o)[8]) {
;     const v4u v = *(const v4u*)(p + 8 * c);
;     const float um = c > 0 ? bf2f(p[8 * c - 1]) : 0.f, up = 8 * c + 8 < n ? bf2f(p[8 * c + 8]) : 0.f;
;     const float u0 = bflo(v.x), u1 = bfhi(v.x), u2 = bflo(v.y), u3 = bfhi(v.y), u4 = bflo(v.z), u5 = bfhi(v.z), u6 = bflo(v.w), u7 = bfhi(v.w);
;     o[0] = w0 * um + w1 * u0 + w2 * u1 + b; o[1] = w0 * u0 + w1 * u1 + w2 * u2 + b; o[2] = w0 * u1 + w1 * u2 + w2 * u3 + b; o[3] = w0 * u2 + w1 * u3 + w2 * u4 + b;
;     o[4] = w0 * u3 + w1 * u4 + w2 * u5 + b; o[5] = w0 * u4 + w1 * u5 + w2 * u6 + b; o[6] = w0 * u5 + w1 * u6 + w2 * u7 + b; o[7] = w0 * u6 + w1 * u7 + w2 * up + b;
; }
.LBB0_563:
	s_or_b64 exec, exec, s[10:11]
	s_and_saveexec_b64 s[10:11], s[46:47]
	s_cbranch_execz .LBB0_556
	global_load_ushort v9, v[10:11], off offset:16
	s_branch .LBB0_556

; __device__ __forceinline__ float bf2f(bf16_t u) { return __uint_as_float((unsigned)u << 16); }
; __device__ __forceinline__ float bflo(unsigned w) { return __uint_as_float(w << 16); }
; __device__ __forceinline__ float bfhi(unsigned w) { return __uint_as_float(w & 0xffff0000u); }
; #define YH ((float*)(wsb(a.ws) + WS_YH))
; __device__ __forceinline__ void conv8(const bf16_t* p, int c, int n, float w0, float w1, float w2, float b, float (&o)[8]) {
;     const v4u v = *(const v4u*)(p + 8 * c);
;     const float um = c > 0 ? bf2f(p[8 * c - 1]) : 0.f, up = 8 * c + 8 < n ? bf2f(p[8 * c + 8]) : 0.f;
;     const float u0 = bflo(v.x), u1 = bfhi(v.x), u2 = bflo(v.y), u3 = bfhi(v.y), u4 = bflo(v.z), u5 = bfhi(v.z), u6 = bflo(v.w), u7 = bfhi(v.w);
;     o[0] = w0 * um + w1 * u0 + w2 * u1 + b; o[1] = w0 * u0 + w1 * u1 + w2 * u2 + b; o[2] = w0 * u1 + w1 * u2 + w2 * u3 + b; o[3] = w0 * u2 + w1 * u3 + w2 * u4 + b;
;     o[4] = w0 * u3 + w1 * u4 + w2 * u5 + b; o[5] = w0 * u4 + w1 * u5 + w2 * u6 + b; o[6] = w0 * u5 + w1 * u6 + w2 * u7 + b; o[7] = w0 * u6 + w1 * u7 + w2 * up + b;
; }
; __global__ void __launch_bounds__(NTHR, 2) fwd_mega(Args a) {
;     ...
;                     for (int k = 0; k < 2; ++k) { const int ch = 64 * (wave + 8 * k) + cw; float x0_[8], x1_[8];
;                         conv8(pv0 + 512 * 8192, ch, 8192, wb0, wb1, wb2, bb, x0_); conv8(pv1 + 512 * 8192, ch, 8192, wb0, wb1, wb2, bb, x1_);
;                         f32x4 o0a, o0b, o1a, o1b;
; #pragma unroll
;                         for (int e = 0; e < 4; ++e) { const cf ca = X[PX(8 * ch + e)], cb2 = X[PX(8 * ch + 4 + e)]; o0a[e] = x0_[e] * ca.x; o1a[e] = x1_[e] * ca.y; o0b[e] = x0_[4 + e] * cb2.x; o1b[e] = x1_[4 + e] * cb2.y; }
;                         float* y0p = YH + ((size_t)b0 * 256 + c) * 8192 + 8 * ch; float* y1p = YH + ((size_t)b1 * 256 + c) * 8192 + 8 * ch;
;                         *(f32x4*)y0p = o0a; *(f32x4*)(y0p + 4) = o0b; *(f32x4*)y1p = o1a; *(f32x4*)(y1p + 4) = o1b; }
.LBB0_580:
	s_or_b64 exec, exec, s[36:37]
	s_waitcnt vmcnt(0) lgkmcnt(0)
	v_lshlrev_b32_e32 v15, 16, v15
	v_lshlrev_b32_e32 v5, 16, v5
	v_lshlrev_b32_e32 v13, 16, v13
	v_lshlrev_b32_e32 v11, 16, v11
	v_and_b32_e32 v170, 0xffff0000, v0
	v_mov_b32_e32 v14, v170
	v_lshlrev_b32_e32 v4, 16, v0
	v_pk_mul_f32 v[14:15], v[148:149], v[14:15]
	v_lshlrev_b32_e32 v171, 16, v1
	v_pk_fma_f32 v[14:15], v[148:149], v[4:5], v[14:15] op_sel:[0,0,1] op_sel_hi:[1,0,0]
	v_and_b32_e32 v153, 0xffff0000, v3
	v_pk_fma_f32 v[14:15], v[144:145], v[170:171], v[14:15]
	v_and_b32_e32 v173, 16, v3
	v_pk_add_f32 v[178:179], v[130:131], v[14:15]
	v_and_b32_e32 v15, 16, v2
	v_and_b32_e32 v14, 0xffff0000, v1
	v_lshlrev_b32_e32 v1, 16, v2
	v_mov_b32_e32 v0, v14
	v_and_b32_e32 v172, 0xffff0000, v2
	v_lshlrev_b32_e32 v175, 16, v3
	v_pk_mov_b32 v[2:3], v[170:171], v[14:15] op_sel:[1,0]
	v_mov_b32_e32 v174, v172
	v_pk_mov_b32 v[172:173], v[0:1], v[172:173] op_sel:[1,0]
	v_pk_mul_f32 v[2:3], v[146:147], v[2:3]
	v_pk_mul_f32 v[14:15], v[146:147], v[172:173]
	v_pk_fma_f32 v[2:3], v[126:127], v[170:171], v[2:3]
	v_mov_b32_e32 v152, v175
	v_pk_fma_f32 v[2:3], v[144:145], v[0:1], v[2:3]
	v_pk_fma_f32 v[0:1], v[126:127], v[0:1], v[14:15]
	v_mov_b32_e32 v4, v153
	v_pk_fma_f32 v[0:1], v[144:145], v[174:175], v[0:1]
	v_lshlrev_b32_e32 v183, 16, v9
	v_pk_add_f32 v[180:181], v[130:131], v[0:1]
	v_pk_mul_f32 v[0:1], v[146:147], v[152:153]
	v_and_b32_e32 v152, 0xffff0000, v6
	v_pk_fma_f32 v[0:1], v[126:127], v[174:175], v[0:1]
	v_lshlrev_b32_e32 v153, 16, v7
	v_pk_fma_f32 v[0:1], v[144:145], v[4:5], v[0:1]
	v_lshlrev_b32_e32 v4, 3, v150
	v_pk_add_f32 v[14:15], v[130:131], v[0:1]
	v_and_b32_e32 v1, -8, v12
	v_add3_u32 v184, 0, v1, v4
	ds_read2_b64 v[170:173], v184 offset1:1
	ds_read2_b64 v[174:177], v184 offset0:4 offset1:5
	v_mov_b32_e32 v12, v152
	v_lshlrev_b32_e32 v0, 16, v6
	v_pk_mul_f32 v[12:13], v[148:149], v[12:13]
	s_waitcnt lgkmcnt(1)
	v_mov_b32_e32 v4, v170
	v_mov_b32_e32 v5, v172
	v_pk_mul_f32 v[4:5], v[4:5], v[178:179]
	v_pk_fma_f32 v[0:1], v[148:149], v[0:1], v[12:13] op_sel:[0,0,1] op_sel_hi:[1,0,0]
	s_waitcnt lgkmcnt(0)
	v_mov_b32_e32 v12, v174
	v_mov_b32_e32 v13, v176
	v_and_b32_e32 v178, 0xffff0000, v7
	v_pk_mul_f32 v[12:13], v[12:13], v[180:181]
	v_lshlrev_b32_e32 v181, 16, v8
	v_mov_b32_e32 v180, v178
	v_and_b32_e32 v7, 16, v9
	v_and_b32_e32 v6, 0xffff0000, v8
	v_mov_b32_e32 v182, v6
	v_pk_mov_b32 v[6:7], v[180:181], v[6:7] op_sel:[1,0]
	v_pk_fma_f32 v[0:1], v[144:145], v[152:153], v[0:1]
	v_pk_mul_f32 v[6:7], v[146:147], v[6:7]
	v_pk_add_f32 v[0:1], v[130:131], v[0:1]
	v_pk_fma_f32 v[6:7], v[126:127], v[180:181], v[6:7]
	v_mov_b32_e32 v172, v171
	v_pk_fma_f32 v[6:7], v[144:145], v[182:183], v[6:7]
	v_mov_b32_e32 v176, v175
	v_pk_add_f32 v[6:7], v[130:131], v[6:7]
	v_and_b32_e32 v10, 0xffff0000, v9
	v_pk_mul_f32 v[0:1], v[172:173], v[0:1]
	v_and_b32_e32 v179, 16, v8
	v_pk_mul_f32 v[8:9], v[176:177], v[6:7]
	ds_read2_b64 v[170:173], v184 offset0:2 offset1:3
	ds_read2_b64 v[174:177], v184 offset0:6 offset1:7
	v_pk_add_f32 v[2:3], v[130:131], v[2:3]
	s_xor_b64 s[36:37], s[60:61], -1
	s_mov_b64 s[34:35], s[58:59]
	s_waitcnt lgkmcnt(1)
	v_mov_b32_e32 v6, v170
	v_mov_b32_e32 v7, v172
	v_pk_mul_f32 v[6:7], v[6:7], v[2:3]
	v_pk_mov_b32 v[2:3], v[152:153], v[178:179] op_sel:[1,0]
	s_add_u32 s23, s34, s10
	v_pk_mul_f32 v[2:3], v[146:147], v[2:3]
	s_addc_u32 s35, s35, s11
	v_pk_fma_f32 v[2:3], v[126:127], v[152:153], v[2:3]
	s_waitcnt lgkmcnt(0)
	v_mov_b32_e32 v152, v174
	v_mov_b32_e32 v153, v176
	v_pk_mul_f32 v[14:15], v[152:153], v[14:15]
	v_mov_b32_e32 v152, v183
	v_mov_b32_e32 v153, v10
	v_pk_mul_f32 v[152:153], v[146:147], v[152:153]
	s_add_u32 s34, s23, s48
	v_pk_fma_f32 v[152:153], v[126:127], v[182:183], v[152:153]
	s_addc_u32 s35, s35, s49
	v_lshlrev_b64 v[150:151], 2, v[150:151]
	v_pk_fma_f32 v[10:11], v[144:145], v[10:11], v[152:153]
	v_lshl_add_u64 v[152:153], s[34:35], 0, v[150:151]
	s_mov_b64 s[34:35], s[58:59]
	s_add_u32 s23, s34, s12
	s_addc_u32 s35, s35, s13
	s_add_u32 s34, s23, s48
	s_mov_b32 s23, 0xd500000
	v_mov_b32_e32 v172, v171
	v_lshl_add_u64 v[170:171], v[152:153], 0, s[26:27]
	s_addc_u32 s35, s35, s49
	v_add_co_u32_e32 v152, vcc, s23, v152
	v_lshl_add_u64 v[150:151], s[34:35], 0, v[150:151]
	s_nop 0
	v_addc_co_u32_e32 v153, vcc, 0, v153, vcc
	v_pk_fma_f32 v[2:3], v[144:145], v[180:181], v[2:3]
	global_store_dwordx4 v[152:153], v[4:7], off
	global_store_dwordx4 v[170:171], v[12:15], off offset:16
	v_pk_add_f32 v[2:3], v[130:131], v[2:3]
	v_add_co_u32_e32 v4, vcc, 0xd500000, v150
	v_pk_mul_f32 v[2:3], v[172:173], v[2:3]
	s_nop 0
	v_addc_co_u32_e32 v5, vcc, 0, v151, vcc
	v_pk_add_f32 v[10:11], v[130:131], v[10:11]
	v_mov_b32_e32 v176, v175
	s_movk_i32 s23, 0x200
	s_mov_b64 s[60:61], 0
	s_and_b64 vcc, exec, s[36:37]
	v_pk_mul_f32 v[10:11], v[176:177], v[10:11]
	v_lshl_add_u64 v[172:173], v[150:151], 0, s[26:27]
	global_store_dwordx4 v[4:5], v[0:3], off
	global_store_dwordx4 v[172:173], v[8:11], off offset:16
	s_cbranch_vccnz .LBB0_530
.LBB0_581:
	v_add_u32_e32 v12, s23, v158
	v_lshlrev_b32_e32 v150, 3, v12
	v_ashrrev_i32_e32 v151, 31, v150
	v_lshl_add_u64 v[6:7], v[150:151], 1, s[4:5]
	global_load_dwordx4 v[0:3], v[6:7], off
	v_cmp_lt_i32_e32 vcc, 0, v12
	v_mov_b32_e32 v5, 0
	v_mov_b32_e32 v15, 0
	s_and_saveexec_b64 s[36:37], vcc
	s_cbranch_execz .LBB0_583
	v_add_co_u32_e64 v8, s[46:47], -2, v6
	s_nop 1
	v_addc_co_u32_e64 v9, s[46:47], -1, v7, s[46:47]
	global_load_ushort v15, v[8:9], off
.LBB0_583:
	s_or_b64 exec, exec, s[36:37]
	v_cmp_gt_i32_e64 s[46:47], s57, v12
	s_and_saveexec_b64 s[36:37], s[46:47]
	s_cbranch_execz .LBB0_585
	global_load_ushort v5, v[6:7], off offset:16
.LBB0_585:
	s_or_b64 exec, exec, s[36:37]
	v_lshl_add_u64 v[152:153], v[150:151], 1, s[6:7]
	global_load_dwordx4 v[6:9], v[152:153], off
	v_mov_b32_e32 v11, 0
	v_mov_b32_e32 v13, 0
	s_and_saveexec_b64 s[36:37], vcc
	s_cbranch_execz .LBB0_587
	v_add_co_u32_e32 v170, vcc, -2, v152
	s_nop 1
	v_addc_co_u32_e32 v171, vcc, -1, v153, vcc
	global_load_ushort v13, v[170:171], off
.LBB0_587:
	s_or_b64 exec, exec, s[36:37]
	s_and_saveexec_b64 s[36:37], s[46:47]
	s_cbranch_execz .LBB0_580
	global_load_ushort v11, v[152:153], off offset:16
	s_branch .LBB0_580
